# L2 residency (energy per MFMA): weight-tile LDS-DMA loads of the up GEMM K-loop marked non-temporal so streamed weights do not evict the activation tiles shared across column tiles (timing-only)
# baseline (speedup 1.0000x reference)
.LBB0_389:
	s_ashr_i32 s29, s28, 31
	s_lshl_b64 s[4:5], s[28:29], 19
	s_add_u32 s30, s12, s4
	s_addc_u32 s31, s13, s5
	s_and_b64 s[4:5], s[40:41], exec
	s_cselect_b32 s29, s31, s43
	s_cselect_b32 vcc_lo, s30, s42
	s_ashr_i32 s37, s36, 31
	s_lshl_b64 s[4:5], s[36:37], 19
	s_add_u32 s34, s17, s4
	s_addc_u32 s35, s70, s5
	s_and_b64 s[4:5], s[40:41], exec
	s_cselect_b32 s37, s35, s39
	s_cselect_b32 vcc_hi, s34, s38
	s_add_u32 s59, s38, 0x100
	v_mov_b32_e32 v74, 0
	s_addc_u32 s72, s39, 0
	s_mov_b32 s73, -2
	s_add_u32 s38, s42, 0x100
	s_addc_u32 s39, s43, 0
	s_add_i32 s4, 0, 0x10000
	s_cmp_eq_u32 s73, 12
	s_cselect_b32 s69, s29, s39
	s_cselect_b32 s68, vcc_lo, s38
	s_cselect_b32 s67, s37, s72
	s_cselect_b32 s66, vcc_hi, s59
	s_add_i32 s6, 0, 0x14000
	v_add_u32_e32 v142, s4, v251
	v_add_u32_e32 v158, s6, v251
	ds_read_b128 v[130:133], v142
	ds_read_b128 v[134:137], v142 offset:1024
	ds_read_b128 v[138:141], v142 offset:2048
	ds_read_b128 v[142:145], v142 offset:3072
	ds_read_b128 v[146:149], v158
	ds_read_b128 v[150:153], v158 offset:1024
	ds_read_b128 v[154:157], v158 offset:2048
	ds_read_b128 v[158:161], v158 offset:3072
	v_lshl_add_u64 v[194:195], s[42:43], 0, v[228:229]
	s_add_i32 m0, s75, 0xc000
	ds_read_b128 v[162:165], v244
	ds_read_b128 v[166:169], v244 offset:1024
	ds_read_b128 v[170:173], v244 offset:2048
	ds_read_b128 v[174:177], v244 offset:3072
	ds_read_b128 v[178:181], v244 offset:4096
	ds_read_b128 v[182:185], v244 offset:5120
	ds_read_b128 v[186:189], v244 offset:6144
	ds_read_b128 v[190:193], v244 offset:7168
	global_load_lds_dwordx4 v[194:195], off
	v_lshl_add_u64 v[194:195], s[42:43], 0, v[230:231]
	s_add_i32 m0, s75, 0xe000
	s_nop 0
	global_load_lds_dwordx4 v[194:195], off
	s_waitcnt vmcnt(8)
	s_waitcnt lgkmcnt(0)
	s_barrier
	s_setprio 1
	s_waitcnt lgkmcnt(0)
	v_mfma_f32_16x16x32_bf16 v[114:117], v[130:133], v[162:165], 0
	v_mfma_f32_16x16x32_bf16 v[122:125], v[138:141], v[162:165], 0
	v_mfma_f32_16x16x32_bf16 v[118:121], v[130:133], v[170:173], 0
	v_mfma_f32_16x16x32_bf16 v[126:129], v[138:141], v[170:173], 0
	v_mfma_f32_16x16x32_bf16 v[54:57], v[130:133], v[178:181], 0
	v_mfma_f32_16x16x32_bf16 v[70:73], v[138:141], v[178:181], 0
	v_mfma_f32_16x16x32_bf16 v[50:53], v[130:133], v[186:189], 0
	v_mfma_f32_16x16x32_bf16 v[66:69], v[138:141], v[186:189], 0
	v_mfma_f32_16x16x32_bf16 v[114:117], v[134:137], v[166:169], v[114:117]
	v_mfma_f32_16x16x32_bf16 v[122:125], v[142:145], v[166:169], v[122:125]
	v_mfma_f32_16x16x32_bf16 v[118:121], v[134:137], v[174:177], v[118:121]
	v_mfma_f32_16x16x32_bf16 v[126:129], v[142:145], v[174:177], v[126:129]
	v_mfma_f32_16x16x32_bf16 v[54:57], v[134:137], v[182:185], v[54:57]
	v_mfma_f32_16x16x32_bf16 v[70:73], v[142:145], v[182:185], v[70:73]
	v_mfma_f32_16x16x32_bf16 v[50:53], v[134:137], v[190:193], v[50:53]
	v_mfma_f32_16x16x32_bf16 v[66:69], v[142:145], v[190:193], v[66:69]
	s_setprio 0
	s_setprio 1
	v_mfma_f32_16x16x32_bf16 v[106:109], v[146:149], v[162:165], 0
	v_mfma_f32_16x16x32_bf16 v[42:45], v[154:157], v[162:165], 0
	v_mfma_f32_16x16x32_bf16 v[110:113], v[146:149], v[170:173], 0
	v_mfma_f32_16x16x32_bf16 v[46:49], v[154:157], v[170:173], 0
	v_mfma_f32_16x16x32_bf16 v[30:33], v[146:149], v[178:181], 0
	v_mfma_f32_16x16x32_bf16 v[14:17], v[154:157], v[178:181], 0
	v_mfma_f32_16x16x32_bf16 v[26:29], v[146:149], v[186:189], 0
	v_mfma_f32_16x16x32_bf16 v[10:13], v[154:157], v[186:189], 0
	v_mfma_f32_16x16x32_bf16 v[106:109], v[150:153], v[166:169], v[106:109]
	v_mfma_f32_16x16x32_bf16 v[42:45], v[158:161], v[166:169], v[42:45]
	v_mfma_f32_16x16x32_bf16 v[110:113], v[150:153], v[174:177], v[110:113]
	v_mfma_f32_16x16x32_bf16 v[46:49], v[158:161], v[174:177], v[46:49]
	v_mfma_f32_16x16x32_bf16 v[30:33], v[150:153], v[182:185], v[30:33]
	v_mfma_f32_16x16x32_bf16 v[14:17], v[158:161], v[182:185], v[14:17]
	v_mfma_f32_16x16x32_bf16 v[26:29], v[150:153], v[190:193], v[26:29]
	s_barrier
	v_mfma_f32_16x16x32_bf16 v[10:13], v[158:161], v[190:193], v[10:13]
	s_setprio 0
	s_add_i32 s4, s4, s74
	v_lshl_add_u64 v[194:195], s[66:67], 0, v[0:1]
	s_mov_b32 m0, s4
	ds_read_b128 v[162:165], v244 offset:16384
	ds_read_b128 v[166:169], v244 offset:17408
	ds_read_b128 v[170:173], v244 offset:18432
	ds_read_b128 v[174:177], v244 offset:19456
	ds_read_b128 v[178:181], v244 offset:20480
	ds_read_b128 v[182:185], v244 offset:21504
	ds_read_b128 v[186:189], v244 offset:22528
	ds_read_b128 v[190:193], v244 offset:23552
	global_load_lds_dwordx4 v[194:195], off nt
	s_add_i32 m0, s4, 0x2000
	s_add_u32 s4, s66, 0x40000
	v_lshl_add_u64 v[196:197], s[66:67], 0, v[224:225]
	s_addc_u32 s5, s67, 0
	s_add_i32 s6, s6, s74
	global_load_lds_dwordx4 v[196:197], off nt
	v_lshl_add_u64 v[198:199], s[4:5], 0, v[0:1]
	s_mov_b32 m0, s6
	v_lshl_add_u64 v[200:201], s[68:69], 0, v[222:223]
	global_load_lds_dwordx4 v[198:199], off nt
	v_lshl_add_u64 v[198:199], s[4:5], 0, v[224:225]
	s_add_i32 m0, s6, 0x2000
	s_nop 0
	global_load_lds_dwordx4 v[198:199], off nt
	v_lshl_add_u64 v[198:199], s[68:69], 0, v[226:227]
	s_mov_b32 m0, s75
	s_nop 0
	global_load_lds_dwordx4 v[198:199], off
	s_mov_b32 m0, s76
	s_nop 0
	global_load_lds_dwordx4 v[200:201], off
	s_waitcnt vmcnt(8)
	s_waitcnt lgkmcnt(0)
	s_barrier
	s_setprio 1
	s_waitcnt lgkmcnt(0)
	v_mfma_f32_16x16x32_bf16 v[38:41], v[130:133], v[162:165], 0
	v_mfma_f32_16x16x32_bf16 v[62:65], v[138:141], v[162:165], 0
	v_mfma_f32_16x16x32_bf16 v[34:37], v[130:133], v[170:173], 0
	v_mfma_f32_16x16x32_bf16 v[58:61], v[138:141], v[170:173], 0
	v_mfma_f32_16x16x32_bf16 v[102:105], v[130:133], v[178:181], 0
	v_mfma_f32_16x16x32_bf16 v[98:101], v[138:141], v[178:181], 0
	v_mfma_f32_16x16x32_bf16 v[94:97], v[130:133], v[186:189], 0
	v_mfma_f32_16x16x32_bf16 v[90:93], v[138:141], v[186:189], 0
	v_mfma_f32_16x16x32_bf16 v[38:41], v[134:137], v[166:169], v[38:41]
	v_mfma_f32_16x16x32_bf16 v[62:65], v[142:145], v[166:169], v[62:65]
	v_mfma_f32_16x16x32_bf16 v[34:37], v[134:137], v[174:177], v[34:37]
	v_mfma_f32_16x16x32_bf16 v[58:61], v[142:145], v[174:177], v[58:61]
	v_mfma_f32_16x16x32_bf16 v[102:105], v[134:137], v[182:185], v[102:105]
	v_mfma_f32_16x16x32_bf16 v[98:101], v[142:145], v[182:185], v[98:101]
	v_mfma_f32_16x16x32_bf16 v[94:97], v[134:137], v[190:193], v[94:97]
	v_mfma_f32_16x16x32_bf16 v[90:93], v[142:145], v[190:193], v[90:93]
	s_setprio 0
	s_setprio 1
	v_mfma_f32_16x16x32_bf16 v[22:25], v[146:149], v[162:165], 0
	v_mfma_f32_16x16x32_bf16 v[6:9], v[154:157], v[162:165], 0
	v_mfma_f32_16x16x32_bf16 v[18:21], v[146:149], v[170:173], 0
	v_mfma_f32_16x16x32_bf16 v[2:5], v[154:157], v[170:173], 0
	v_mfma_f32_16x16x32_bf16 v[86:89], v[146:149], v[178:181], 0
	v_mfma_f32_16x16x32_bf16 v[82:85], v[154:157], v[178:181], 0
	v_mfma_f32_16x16x32_bf16 v[78:81], v[146:149], v[186:189], 0
	v_mfma_f32_16x16x32_bf16 v[74:77], v[154:157], v[186:189], 0
	v_mfma_f32_16x16x32_bf16 v[22:25], v[150:153], v[166:169], v[22:25]
	v_mfma_f32_16x16x32_bf16 v[6:9], v[158:161], v[166:169], v[6:9]
	v_mfma_f32_16x16x32_bf16 v[18:21], v[150:153], v[174:177], v[18:21]
	v_mfma_f32_16x16x32_bf16 v[2:5], v[158:161], v[174:177], v[2:5]
	v_mfma_f32_16x16x32_bf16 v[86:89], v[150:153], v[182:185], v[86:89]
	v_mfma_f32_16x16x32_bf16 v[82:85], v[158:161], v[182:185], v[82:85]
	v_mfma_f32_16x16x32_bf16 v[78:81], v[150:153], v[190:193], v[78:81]
	s_barrier
	v_mfma_f32_16x16x32_bf16 v[74:77], v[158:161], v[190:193], v[74:77]
	s_setprio 0
	s_add_i32 s6, 0, 0x18000
	s_add_i32 s7, 0, 0x1c000
	v_add_u32_e32 v142, s6, v251
	v_add_u32_e32 v158, s7, v251
	ds_read_b128 v[130:133], v142
	ds_read_b128 v[134:137], v142 offset:1024
	ds_read_b128 v[138:141], v142 offset:2048
	ds_read_b128 v[142:145], v142 offset:3072
	ds_read_b128 v[146:149], v158
	ds_read_b128 v[150:153], v158 offset:1024
	ds_read_b128 v[154:157], v158 offset:2048
	ds_read_b128 v[158:161], v158 offset:3072
	s_add_u32 s4, s68, 0x2000
	s_addc_u32 s5, s69, 0
	s_mov_b32 m0, s77
	v_lshl_add_u64 v[202:203], s[4:5], 0, v[226:227]
	ds_read_b128 v[162:165], v244 offset:32768
	ds_read_b128 v[166:169], v244 offset:33792
	ds_read_b128 v[170:173], v244 offset:34816
	ds_read_b128 v[174:177], v244 offset:35840
	ds_read_b128 v[178:181], v244 offset:36864
	ds_read_b128 v[182:185], v244 offset:37888
	ds_read_b128 v[186:189], v244 offset:38912
	ds_read_b128 v[190:193], v244 offset:39936
	global_load_lds_dwordx4 v[202:203], off
	v_lshl_add_u64 v[202:203], s[4:5], 0, v[222:223]
	s_mov_b32 m0, s78
	s_nop 0
	global_load_lds_dwordx4 v[202:203], off
	s_waitcnt vmcnt(8)
	s_waitcnt lgkmcnt(0)
	s_barrier
	s_setprio 1
	s_waitcnt lgkmcnt(0)
	v_mfma_f32_16x16x32_bf16 v[114:117], v[130:133], v[162:165], v[114:117]
	v_mfma_f32_16x16x32_bf16 v[122:125], v[138:141], v[162:165], v[122:125]
	v_mfma_f32_16x16x32_bf16 v[118:121], v[130:133], v[170:173], v[118:121]
	v_mfma_f32_16x16x32_bf16 v[126:129], v[138:141], v[170:173], v[126:129]
	v_mfma_f32_16x16x32_bf16 v[54:57], v[130:133], v[178:181], v[54:57]
	v_mfma_f32_16x16x32_bf16 v[70:73], v[138:141], v[178:181], v[70:73]
	v_mfma_f32_16x16x32_bf16 v[50:53], v[130:133], v[186:189], v[50:53]
	v_mfma_f32_16x16x32_bf16 v[66:69], v[138:141], v[186:189], v[66:69]
	v_mfma_f32_16x16x32_bf16 v[114:117], v[134:137], v[166:169], v[114:117]
	v_mfma_f32_16x16x32_bf16 v[122:125], v[142:145], v[166:169], v[122:125]
	v_mfma_f32_16x16x32_bf16 v[118:121], v[134:137], v[174:177], v[118:121]
	v_mfma_f32_16x16x32_bf16 v[126:129], v[142:145], v[174:177], v[126:129]
	v_mfma_f32_16x16x32_bf16 v[54:57], v[134:137], v[182:185], v[54:57]
	v_mfma_f32_16x16x32_bf16 v[70:73], v[142:145], v[182:185], v[70:73]
	v_mfma_f32_16x16x32_bf16 v[50:53], v[134:137], v[190:193], v[50:53]
	v_mfma_f32_16x16x32_bf16 v[66:69], v[142:145], v[190:193], v[66:69]
	s_setprio 0
	s_setprio 1
	v_mfma_f32_16x16x32_bf16 v[106:109], v[146:149], v[162:165], v[106:109]
	v_mfma_f32_16x16x32_bf16 v[42:45], v[154:157], v[162:165], v[42:45]
	v_mfma_f32_16x16x32_bf16 v[110:113], v[146:149], v[170:173], v[110:113]
	v_mfma_f32_16x16x32_bf16 v[46:49], v[154:157], v[170:173], v[46:49]
	v_mfma_f32_16x16x32_bf16 v[30:33], v[146:149], v[178:181], v[30:33]
	v_mfma_f32_16x16x32_bf16 v[14:17], v[154:157], v[178:181], v[14:17]
	v_mfma_f32_16x16x32_bf16 v[26:29], v[146:149], v[186:189], v[26:29]
	v_mfma_f32_16x16x32_bf16 v[10:13], v[154:157], v[186:189], v[10:13]
	v_mfma_f32_16x16x32_bf16 v[106:109], v[150:153], v[166:169], v[106:109]
	v_mfma_f32_16x16x32_bf16 v[42:45], v[158:161], v[166:169], v[42:45]
	v_mfma_f32_16x16x32_bf16 v[110:113], v[150:153], v[174:177], v[110:113]
	v_mfma_f32_16x16x32_bf16 v[46:49], v[158:161], v[174:177], v[46:49]
	v_mfma_f32_16x16x32_bf16 v[30:33], v[150:153], v[182:185], v[30:33]
	v_mfma_f32_16x16x32_bf16 v[14:17], v[158:161], v[182:185], v[14:17]
	v_mfma_f32_16x16x32_bf16 v[26:29], v[150:153], v[190:193], v[26:29]
	s_barrier
	v_mfma_f32_16x16x32_bf16 v[10:13], v[158:161], v[190:193], v[10:13]
	s_setprio 0
	s_add_i32 s4, s6, s74
	v_lshl_add_u64 v[194:195], v[194:195], 0, s[82:83]
	s_mov_b32 m0, s4
	ds_read_b128 v[162:165], v244 offset:49152
	ds_read_b128 v[166:169], v244 offset:50176
	ds_read_b128 v[170:173], v244 offset:51200
	ds_read_b128 v[174:177], v244 offset:52224
	ds_read_b128 v[178:181], v244 offset:53248
	ds_read_b128 v[182:185], v244 offset:54272
	ds_read_b128 v[186:189], v244 offset:55296
	ds_read_b128 v[190:193], v244 offset:56320
	global_load_lds_dwordx4 v[194:195], off nt
	s_add_i32 m0, s4, 0x2000
	s_add_u32 s4, s66, 0x40080
	v_lshl_add_u64 v[194:195], v[196:197], 0, s[82:83]
	s_addc_u32 s5, s67, 0
	s_add_i32 s6, s7, s74
	global_load_lds_dwordx4 v[194:195], off nt
	v_lshl_add_u64 v[194:195], s[4:5], 0, v[0:1]
	s_mov_b32 m0, s6
	s_nop 0
	global_load_lds_dwordx4 v[194:195], off nt
	v_lshl_add_u64 v[194:195], s[4:5], 0, v[224:225]
	s_add_i32 m0, s6, 0x2000
	s_nop 0
	global_load_lds_dwordx4 v[194:195], off nt
	v_lshl_add_u64 v[194:195], v[198:199], 0, s[82:83]
	s_mov_b32 m0, s94
	s_nop 0
	global_load_lds_dwordx4 v[194:195], off
	v_lshl_add_u64 v[194:195], v[200:201], 0, s[82:83]
	s_mov_b32 m0, s95
	s_nop 0
	global_load_lds_dwordx4 v[194:195], off
	s_waitcnt vmcnt(8)
	s_waitcnt lgkmcnt(0)
	s_barrier
	s_setprio 1
	s_waitcnt lgkmcnt(0)
	v_mfma_f32_16x16x32_bf16 v[38:41], v[130:133], v[162:165], v[38:41]
	v_mfma_f32_16x16x32_bf16 v[62:65], v[138:141], v[162:165], v[62:65]
	v_mfma_f32_16x16x32_bf16 v[34:37], v[130:133], v[170:173], v[34:37]
	v_mfma_f32_16x16x32_bf16 v[58:61], v[138:141], v[170:173], v[58:61]
	v_mfma_f32_16x16x32_bf16 v[102:105], v[130:133], v[178:181], v[102:105]
	v_mfma_f32_16x16x32_bf16 v[98:101], v[138:141], v[178:181], v[98:101]
	v_mfma_f32_16x16x32_bf16 v[94:97], v[130:133], v[186:189], v[94:97]
	v_mfma_f32_16x16x32_bf16 v[90:93], v[138:141], v[186:189], v[90:93]
	v_mfma_f32_16x16x32_bf16 v[38:41], v[134:137], v[166:169], v[38:41]
	v_mfma_f32_16x16x32_bf16 v[62:65], v[142:145], v[166:169], v[62:65]
	v_mfma_f32_16x16x32_bf16 v[34:37], v[134:137], v[174:177], v[34:37]
	v_mfma_f32_16x16x32_bf16 v[58:61], v[142:145], v[174:177], v[58:61]
	v_mfma_f32_16x16x32_bf16 v[102:105], v[134:137], v[182:185], v[102:105]
	v_mfma_f32_16x16x32_bf16 v[98:101], v[142:145], v[182:185], v[98:101]
	v_mfma_f32_16x16x32_bf16 v[94:97], v[134:137], v[190:193], v[94:97]
	v_mfma_f32_16x16x32_bf16 v[90:93], v[142:145], v[190:193], v[90:93]
	s_setprio 0
	s_setprio 1
	v_mfma_f32_16x16x32_bf16 v[22:25], v[146:149], v[162:165], v[22:25]
	v_mfma_f32_16x16x32_bf16 v[6:9], v[154:157], v[162:165], v[6:9]
	v_mfma_f32_16x16x32_bf16 v[18:21], v[146:149], v[170:173], v[18:21]
	v_mfma_f32_16x16x32_bf16 v[2:5], v[154:157], v[170:173], v[2:5]
	v_mfma_f32_16x16x32_bf16 v[86:89], v[146:149], v[178:181], v[86:89]
	v_mfma_f32_16x16x32_bf16 v[82:85], v[154:157], v[178:181], v[82:85]
	v_mfma_f32_16x16x32_bf16 v[78:81], v[146:149], v[186:189], v[78:81]
	v_mfma_f32_16x16x32_bf16 v[74:77], v[154:157], v[186:189], v[74:77]
	v_mfma_f32_16x16x32_bf16 v[22:25], v[150:153], v[166:169], v[22:25]
	v_mfma_f32_16x16x32_bf16 v[6:9], v[158:161], v[166:169], v[6:9]
	v_mfma_f32_16x16x32_bf16 v[18:21], v[150:153], v[174:177], v[18:21]
	v_mfma_f32_16x16x32_bf16 v[2:5], v[158:161], v[174:177], v[2:5]
	v_mfma_f32_16x16x32_bf16 v[86:89], v[150:153], v[182:185], v[86:89]
	v_mfma_f32_16x16x32_bf16 v[82:85], v[158:161], v[182:185], v[82:85]
	v_mfma_f32_16x16x32_bf16 v[78:81], v[150:153], v[190:193], v[78:81]
	s_barrier
	v_mfma_f32_16x16x32_bf16 v[74:77], v[158:161], v[190:193], v[74:77]
	s_setprio 0
	s_add_i32 s73, s73, 2
	s_add_u32 s59, s59, 0x100
	s_addc_u32 s72, s72, 0
	s_cmp_gt_u32 s73, 13
	s_mov_b64 s[42:43], s[38:39]
.LBB0_390:
	s_add_u32 s38, s42, 0x100
	s_addc_u32 s39, s43, 0
	s_add_i32 s4, 0, 0x10000
	s_cmp_eq_u32 s73, 12
	s_cselect_b32 s69, s29, s39
	s_cselect_b32 s68, vcc_lo, s38
	s_cselect_b32 s67, s37, s72
	s_cselect_b32 s66, vcc_hi, s59
	s_add_i32 s6, 0, 0x14000
	v_add_u32_e32 v142, s4, v251
	v_add_u32_e32 v158, s6, v251
	ds_read_b128 v[130:133], v142
	ds_read_b128 v[134:137], v142 offset:1024
	ds_read_b128 v[138:141], v142 offset:2048
	ds_read_b128 v[142:145], v142 offset:3072
	ds_read_b128 v[146:149], v158
	ds_read_b128 v[150:153], v158 offset:1024
	ds_read_b128 v[154:157], v158 offset:2048
	ds_read_b128 v[158:161], v158 offset:3072
	v_lshl_add_u64 v[194:195], s[42:43], 0, v[228:229]
	s_add_i32 m0, s75, 0xc000
	ds_read_b128 v[162:165], v244
	ds_read_b128 v[166:169], v244 offset:1024
	ds_read_b128 v[170:173], v244 offset:2048
	ds_read_b128 v[174:177], v244 offset:3072
	ds_read_b128 v[178:181], v244 offset:4096
	ds_read_b128 v[182:185], v244 offset:5120
	ds_read_b128 v[186:189], v244 offset:6144
	ds_read_b128 v[190:193], v244 offset:7168
	global_load_lds_dwordx4 v[194:195], off
	v_lshl_add_u64 v[194:195], s[42:43], 0, v[230:231]
	s_add_i32 m0, s75, 0xe000
	s_nop 0
	global_load_lds_dwordx4 v[194:195], off
	s_waitcnt vmcnt(8)
	s_waitcnt lgkmcnt(0)
	s_barrier
	s_setprio 1
	s_waitcnt lgkmcnt(0)
	v_mfma_f32_16x16x32_bf16 v[114:117], v[130:133], v[162:165], v[114:117]
	v_mfma_f32_16x16x32_bf16 v[122:125], v[138:141], v[162:165], v[122:125]
	v_mfma_f32_16x16x32_bf16 v[118:121], v[130:133], v[170:173], v[118:121]
	v_mfma_f32_16x16x32_bf16 v[126:129], v[138:141], v[170:173], v[126:129]
	v_mfma_f32_16x16x32_bf16 v[54:57], v[130:133], v[178:181], v[54:57]
	v_mfma_f32_16x16x32_bf16 v[70:73], v[138:141], v[178:181], v[70:73]
	v_mfma_f32_16x16x32_bf16 v[50:53], v[130:133], v[186:189], v[50:53]
	v_mfma_f32_16x16x32_bf16 v[66:69], v[138:141], v[186:189], v[66:69]
	v_mfma_f32_16x16x32_bf16 v[114:117], v[134:137], v[166:169], v[114:117]
	v_mfma_f32_16x16x32_bf16 v[122:125], v[142:145], v[166:169], v[122:125]
	v_mfma_f32_16x16x32_bf16 v[118:121], v[134:137], v[174:177], v[118:121]
	v_mfma_f32_16x16x32_bf16 v[126:129], v[142:145], v[174:177], v[126:129]
	v_mfma_f32_16x16x32_bf16 v[54:57], v[134:137], v[182:185], v[54:57]
	v_mfma_f32_16x16x32_bf16 v[70:73], v[142:145], v[182:185], v[70:73]
	v_mfma_f32_16x16x32_bf16 v[50:53], v[134:137], v[190:193], v[50:53]
	v_mfma_f32_16x16x32_bf16 v[66:69], v[142:145], v[190:193], v[66:69]
	s_setprio 0
	s_setprio 1
	v_mfma_f32_16x16x32_bf16 v[106:109], v[146:149], v[162:165], v[106:109]
	v_mfma_f32_16x16x32_bf16 v[42:45], v[154:157], v[162:165], v[42:45]
	v_mfma_f32_16x16x32_bf16 v[110:113], v[146:149], v[170:173], v[110:113]
	v_mfma_f32_16x16x32_bf16 v[46:49], v[154:157], v[170:173], v[46:49]
	v_mfma_f32_16x16x32_bf16 v[30:33], v[146:149], v[178:181], v[30:33]
	v_mfma_f32_16x16x32_bf16 v[14:17], v[154:157], v[178:181], v[14:17]
	v_mfma_f32_16x16x32_bf16 v[26:29], v[146:149], v[186:189], v[26:29]
	v_mfma_f32_16x16x32_bf16 v[10:13], v[154:157], v[186:189], v[10:13]
	v_mfma_f32_16x16x32_bf16 v[106:109], v[150:153], v[166:169], v[106:109]
	v_mfma_f32_16x16x32_bf16 v[42:45], v[158:161], v[166:169], v[42:45]
	v_mfma_f32_16x16x32_bf16 v[110:113], v[150:153], v[174:177], v[110:113]
	v_mfma_f32_16x16x32_bf16 v[46:49], v[158:161], v[174:177], v[46:49]
	v_mfma_f32_16x16x32_bf16 v[30:33], v[150:153], v[182:185], v[30:33]
	v_mfma_f32_16x16x32_bf16 v[14:17], v[158:161], v[182:185], v[14:17]
	v_mfma_f32_16x16x32_bf16 v[26:29], v[150:153], v[190:193], v[26:29]
	s_barrier
	v_mfma_f32_16x16x32_bf16 v[10:13], v[158:161], v[190:193], v[10:13]
	s_setprio 0
	s_add_i32 s4, s4, s74
	v_lshl_add_u64 v[194:195], s[66:67], 0, v[0:1]
	s_mov_b32 m0, s4
	ds_read_b128 v[162:165], v244 offset:16384
	ds_read_b128 v[166:169], v244 offset:17408
	ds_read_b128 v[170:173], v244 offset:18432
	ds_read_b128 v[174:177], v244 offset:19456
	ds_read_b128 v[178:181], v244 offset:20480
	ds_read_b128 v[182:185], v244 offset:21504
	ds_read_b128 v[186:189], v244 offset:22528
	ds_read_b128 v[190:193], v244 offset:23552
	global_load_lds_dwordx4 v[194:195], off nt
	s_add_i32 m0, s4, 0x2000
	s_add_u32 s4, s66, 0x40000
	v_lshl_add_u64 v[196:197], s[66:67], 0, v[224:225]
	s_addc_u32 s5, s67, 0
	s_add_i32 s6, s6, s74
	global_load_lds_dwordx4 v[196:197], off nt
	v_lshl_add_u64 v[198:199], s[4:5], 0, v[0:1]
	s_mov_b32 m0, s6
	v_lshl_add_u64 v[200:201], s[68:69], 0, v[222:223]
	global_load_lds_dwordx4 v[198:199], off nt
	v_lshl_add_u64 v[198:199], s[4:5], 0, v[224:225]
	s_add_i32 m0, s6, 0x2000
	s_nop 0
	global_load_lds_dwordx4 v[198:199], off nt
	v_lshl_add_u64 v[198:199], s[68:69], 0, v[226:227]
	s_mov_b32 m0, s75
	s_nop 0
	global_load_lds_dwordx4 v[198:199], off
	s_mov_b32 m0, s76
	s_nop 0
	global_load_lds_dwordx4 v[200:201], off
	s_waitcnt vmcnt(8)
	s_waitcnt lgkmcnt(0)
	s_barrier
	s_setprio 1
	s_waitcnt lgkmcnt(0)
	v_mfma_f32_16x16x32_bf16 v[38:41], v[130:133], v[162:165], v[38:41]
	v_mfma_f32_16x16x32_bf16 v[62:65], v[138:141], v[162:165], v[62:65]
	v_mfma_f32_16x16x32_bf16 v[34:37], v[130:133], v[170:173], v[34:37]
	v_mfma_f32_16x16x32_bf16 v[58:61], v[138:141], v[170:173], v[58:61]
	v_mfma_f32_16x16x32_bf16 v[102:105], v[130:133], v[178:181], v[102:105]
	v_mfma_f32_16x16x32_bf16 v[98:101], v[138:141], v[178:181], v[98:101]
	v_mfma_f32_16x16x32_bf16 v[94:97], v[130:133], v[186:189], v[94:97]
	v_mfma_f32_16x16x32_bf16 v[90:93], v[138:141], v[186:189], v[90:93]
	v_mfma_f32_16x16x32_bf16 v[38:41], v[134:137], v[166:169], v[38:41]
	v_mfma_f32_16x16x32_bf16 v[62:65], v[142:145], v[166:169], v[62:65]
	v_mfma_f32_16x16x32_bf16 v[34:37], v[134:137], v[174:177], v[34:37]
	v_mfma_f32_16x16x32_bf16 v[58:61], v[142:145], v[174:177], v[58:61]
	v_mfma_f32_16x16x32_bf16 v[102:105], v[134:137], v[182:185], v[102:105]
	v_mfma_f32_16x16x32_bf16 v[98:101], v[142:145], v[182:185], v[98:101]
	v_mfma_f32_16x16x32_bf16 v[94:97], v[134:137], v[190:193], v[94:97]
	v_mfma_f32_16x16x32_bf16 v[90:93], v[142:145], v[190:193], v[90:93]
	s_setprio 0
	s_setprio 1
	v_mfma_f32_16x16x32_bf16 v[22:25], v[146:149], v[162:165], v[22:25]
	v_mfma_f32_16x16x32_bf16 v[6:9], v[154:157], v[162:165], v[6:9]
	v_mfma_f32_16x16x32_bf16 v[18:21], v[146:149], v[170:173], v[18:21]
	v_mfma_f32_16x16x32_bf16 v[2:5], v[154:157], v[170:173], v[2:5]
	v_mfma_f32_16x16x32_bf16 v[86:89], v[146:149], v[178:181], v[86:89]
	v_mfma_f32_16x16x32_bf16 v[82:85], v[154:157], v[178:181], v[82:85]
	v_mfma_f32_16x16x32_bf16 v[78:81], v[146:149], v[186:189], v[78:81]
	v_mfma_f32_16x16x32_bf16 v[74:77], v[154:157], v[186:189], v[74:77]
	v_mfma_f32_16x16x32_bf16 v[22:25], v[150:153], v[166:169], v[22:25]
	v_mfma_f32_16x16x32_bf16 v[6:9], v[158:161], v[166:169], v[6:9]
	v_mfma_f32_16x16x32_bf16 v[18:21], v[150:153], v[174:177], v[18:21]
	v_mfma_f32_16x16x32_bf16 v[2:5], v[158:161], v[174:177], v[2:5]
	v_mfma_f32_16x16x32_bf16 v[86:89], v[150:153], v[182:185], v[86:89]
	v_mfma_f32_16x16x32_bf16 v[82:85], v[158:161], v[182:185], v[82:85]
	v_mfma_f32_16x16x32_bf16 v[78:81], v[150:153], v[190:193], v[78:81]
	s_barrier
	v_mfma_f32_16x16x32_bf16 v[74:77], v[158:161], v[190:193], v[74:77]
	s_setprio 0
	s_add_i32 s6, 0, 0x18000
	s_add_i32 s7, 0, 0x1c000
	v_add_u32_e32 v142, s6, v251
	v_add_u32_e32 v158, s7, v251
	ds_read_b128 v[130:133], v142
	ds_read_b128 v[134:137], v142 offset:1024
	ds_read_b128 v[138:141], v142 offset:2048
	ds_read_b128 v[142:145], v142 offset:3072
	ds_read_b128 v[146:149], v158
	ds_read_b128 v[150:153], v158 offset:1024
	ds_read_b128 v[154:157], v158 offset:2048
	ds_read_b128 v[158:161], v158 offset:3072
	s_add_u32 s4, s68, 0x2000
	s_addc_u32 s5, s69, 0
	s_mov_b32 m0, s77
	v_lshl_add_u64 v[202:203], s[4:5], 0, v[226:227]
	ds_read_b128 v[162:165], v244 offset:32768
	ds_read_b128 v[166:169], v244 offset:33792
	ds_read_b128 v[170:173], v244 offset:34816
	ds_read_b128 v[174:177], v244 offset:35840
	ds_read_b128 v[178:181], v244 offset:36864
	ds_read_b128 v[182:185], v244 offset:37888
	ds_read_b128 v[186:189], v244 offset:38912
	ds_read_b128 v[190:193], v244 offset:39936
	global_load_lds_dwordx4 v[202:203], off
	v_lshl_add_u64 v[202:203], s[4:5], 0, v[222:223]
	s_mov_b32 m0, s78
	s_nop 0
	global_load_lds_dwordx4 v[202:203], off
	s_waitcnt vmcnt(8)
	s_waitcnt lgkmcnt(0)
	s_barrier
	s_setprio 1
	s_waitcnt lgkmcnt(0)
	v_mfma_f32_16x16x32_bf16 v[114:117], v[130:133], v[162:165], v[114:117]
	v_mfma_f32_16x16x32_bf16 v[122:125], v[138:141], v[162:165], v[122:125]
	v_mfma_f32_16x16x32_bf16 v[118:121], v[130:133], v[170:173], v[118:121]
	v_mfma_f32_16x16x32_bf16 v[126:129], v[138:141], v[170:173], v[126:129]
	v_mfma_f32_16x16x32_bf16 v[54:57], v[130:133], v[178:181], v[54:57]
	v_mfma_f32_16x16x32_bf16 v[70:73], v[138:141], v[178:181], v[70:73]
	v_mfma_f32_16x16x32_bf16 v[50:53], v[130:133], v[186:189], v[50:53]
	v_mfma_f32_16x16x32_bf16 v[66:69], v[138:141], v[186:189], v[66:69]
	v_mfma_f32_16x16x32_bf16 v[114:117], v[134:137], v[166:169], v[114:117]
	v_mfma_f32_16x16x32_bf16 v[122:125], v[142:145], v[166:169], v[122:125]
	v_mfma_f32_16x16x32_bf16 v[118:121], v[134:137], v[174:177], v[118:121]
	v_mfma_f32_16x16x32_bf16 v[126:129], v[142:145], v[174:177], v[126:129]
	v_mfma_f32_16x16x32_bf16 v[54:57], v[134:137], v[182:185], v[54:57]
	v_mfma_f32_16x16x32_bf16 v[70:73], v[142:145], v[182:185], v[70:73]
	v_mfma_f32_16x16x32_bf16 v[50:53], v[134:137], v[190:193], v[50:53]
	v_mfma_f32_16x16x32_bf16 v[66:69], v[142:145], v[190:193], v[66:69]
	s_setprio 0
	s_setprio 1
	v_mfma_f32_16x16x32_bf16 v[106:109], v[146:149], v[162:165], v[106:109]
	v_mfma_f32_16x16x32_bf16 v[42:45], v[154:157], v[162:165], v[42:45]
	v_mfma_f32_16x16x32_bf16 v[110:113], v[146:149], v[170:173], v[110:113]
	v_mfma_f32_16x16x32_bf16 v[46:49], v[154:157], v[170:173], v[46:49]
	v_mfma_f32_16x16x32_bf16 v[30:33], v[146:149], v[178:181], v[30:33]
	v_mfma_f32_16x16x32_bf16 v[14:17], v[154:157], v[178:181], v[14:17]
	v_mfma_f32_16x16x32_bf16 v[26:29], v[146:149], v[186:189], v[26:29]
	v_mfma_f32_16x16x32_bf16 v[10:13], v[154:157], v[186:189], v[10:13]
	v_mfma_f32_16x16x32_bf16 v[106:109], v[150:153], v[166:169], v[106:109]
	v_mfma_f32_16x16x32_bf16 v[42:45], v[158:161], v[166:169], v[42:45]
	v_mfma_f32_16x16x32_bf16 v[110:113], v[150:153], v[174:177], v[110:113]
	v_mfma_f32_16x16x32_bf16 v[46:49], v[158:161], v[174:177], v[46:49]
	v_mfma_f32_16x16x32_bf16 v[30:33], v[150:153], v[182:185], v[30:33]
	v_mfma_f32_16x16x32_bf16 v[14:17], v[158:161], v[182:185], v[14:17]
	v_mfma_f32_16x16x32_bf16 v[26:29], v[150:153], v[190:193], v[26:29]
	s_barrier
	v_mfma_f32_16x16x32_bf16 v[10:13], v[158:161], v[190:193], v[10:13]
	s_setprio 0
	s_add_i32 s4, s6, s74
	v_lshl_add_u64 v[194:195], v[194:195], 0, s[82:83]
	s_mov_b32 m0, s4
	ds_read_b128 v[162:165], v244 offset:49152
	ds_read_b128 v[166:169], v244 offset:50176
	ds_read_b128 v[170:173], v244 offset:51200
	ds_read_b128 v[174:177], v244 offset:52224
	ds_read_b128 v[178:181], v244 offset:53248
	ds_read_b128 v[182:185], v244 offset:54272
	ds_read_b128 v[186:189], v244 offset:55296
	ds_read_b128 v[190:193], v244 offset:56320
	global_load_lds_dwordx4 v[194:195], off nt
	s_add_i32 m0, s4, 0x2000
	s_add_u32 s4, s66, 0x40080
	v_lshl_add_u64 v[194:195], v[196:197], 0, s[82:83]
	s_addc_u32 s5, s67, 0
	s_add_i32 s6, s7, s74
	global_load_lds_dwordx4 v[194:195], off nt
	v_lshl_add_u64 v[194:195], s[4:5], 0, v[0:1]
	s_mov_b32 m0, s6
	s_nop 0
	global_load_lds_dwordx4 v[194:195], off nt
	v_lshl_add_u64 v[194:195], s[4:5], 0, v[224:225]
	s_add_i32 m0, s6, 0x2000
	s_nop 0
	global_load_lds_dwordx4 v[194:195], off nt
	v_lshl_add_u64 v[194:195], v[198:199], 0, s[82:83]
	s_mov_b32 m0, s94
	s_nop 0
	global_load_lds_dwordx4 v[194:195], off
	v_lshl_add_u64 v[194:195], v[200:201], 0, s[82:83]
	s_mov_b32 m0, s95
	s_nop 0
	global_load_lds_dwordx4 v[194:195], off
	s_waitcnt vmcnt(8)
	s_waitcnt lgkmcnt(0)
	s_barrier
	s_setprio 1
	s_waitcnt lgkmcnt(0)
	v_mfma_f32_16x16x32_bf16 v[38:41], v[130:133], v[162:165], v[38:41]
	v_mfma_f32_16x16x32_bf16 v[62:65], v[138:141], v[162:165], v[62:65]
	v_mfma_f32_16x16x32_bf16 v[34:37], v[130:133], v[170:173], v[34:37]
	v_mfma_f32_16x16x32_bf16 v[58:61], v[138:141], v[170:173], v[58:61]
	v_mfma_f32_16x16x32_bf16 v[102:105], v[130:133], v[178:181], v[102:105]
	v_mfma_f32_16x16x32_bf16 v[98:101], v[138:141], v[178:181], v[98:101]
	v_mfma_f32_16x16x32_bf16 v[94:97], v[130:133], v[186:189], v[94:97]
	v_mfma_f32_16x16x32_bf16 v[90:93], v[138:141], v[186:189], v[90:93]
	v_mfma_f32_16x16x32_bf16 v[38:41], v[134:137], v[166:169], v[38:41]
	v_mfma_f32_16x16x32_bf16 v[62:65], v[142:145], v[166:169], v[62:65]
	v_mfma_f32_16x16x32_bf16 v[34:37], v[134:137], v[174:177], v[34:37]
	v_mfma_f32_16x16x32_bf16 v[58:61], v[142:145], v[174:177], v[58:61]
	v_mfma_f32_16x16x32_bf16 v[102:105], v[134:137], v[182:185], v[102:105]
	v_mfma_f32_16x16x32_bf16 v[98:101], v[142:145], v[182:185], v[98:101]
	v_mfma_f32_16x16x32_bf16 v[94:97], v[134:137], v[190:193], v[94:97]
	v_mfma_f32_16x16x32_bf16 v[90:93], v[142:145], v[190:193], v[90:93]
	s_setprio 0
	s_setprio 1
	v_mfma_f32_16x16x32_bf16 v[22:25], v[146:149], v[162:165], v[22:25]
	v_mfma_f32_16x16x32_bf16 v[6:9], v[154:157], v[162:165], v[6:9]
	v_mfma_f32_16x16x32_bf16 v[18:21], v[146:149], v[170:173], v[18:21]
	v_mfma_f32_16x16x32_bf16 v[2:5], v[154:157], v[170:173], v[2:5]
	v_mfma_f32_16x16x32_bf16 v[86:89], v[146:149], v[178:181], v[86:89]
	v_mfma_f32_16x16x32_bf16 v[82:85], v[154:157], v[178:181], v[82:85]
	v_mfma_f32_16x16x32_bf16 v[78:81], v[146:149], v[186:189], v[78:81]
	v_mfma_f32_16x16x32_bf16 v[74:77], v[154:157], v[186:189], v[74:77]
	v_mfma_f32_16x16x32_bf16 v[22:25], v[150:153], v[166:169], v[22:25]
	v_mfma_f32_16x16x32_bf16 v[6:9], v[158:161], v[166:169], v[6:9]
	v_mfma_f32_16x16x32_bf16 v[18:21], v[150:153], v[174:177], v[18:21]
	v_mfma_f32_16x16x32_bf16 v[2:5], v[158:161], v[174:177], v[2:5]
	v_mfma_f32_16x16x32_bf16 v[86:89], v[150:153], v[182:185], v[86:89]
	v_mfma_f32_16x16x32_bf16 v[82:85], v[158:161], v[182:185], v[82:85]
	v_mfma_f32_16x16x32_bf16 v[78:81], v[150:153], v[190:193], v[78:81]
	s_barrier
	v_mfma_f32_16x16x32_bf16 v[74:77], v[158:161], v[190:193], v[74:77]
	s_setprio 0
	s_add_i32 s73, s73, 2
	s_add_u32 s59, s59, 0x100
	s_addc_u32 s72, s72, 0
	s_cmp_gt_u32 s73, 13
	s_mov_b64 s[42:43], s[38:39]
	s_cbranch_scc0 .LBB0_390
	s_and_b64 vcc, exec, s[50:51]
	s_cbranch_vccz .LBB0_393
	s_barrier
